# v34 + DFT stage 1 (S=8192 loop): every q-tile's results staged through the head of the wave's own LDS slice and stored as four row-contiguous dwordx2 (4 rows x 128 B) instead of 16 rows x 32-B pieces
# speedup vs baseline: 1.0313x; 1.0043x over previous
.LBB0_126:
	s_mul_i32 s2, s23, 0x4800
	s_add_i32 s2, s2, 0
	s_cmpk_lt_i32 s20, 0x1000
	s_cselect_b64 s[10:11], -1, 0
	v_cndmask_b32_e64 v0, 0, 1, s[10:11]
	v_lshrrev_b32_e32 v177, 4, v201
	s_mov_b64 s[8:9], -1
	s_and_b64 vcc, exec, s[6:7]
	v_cmp_ne_u32_e64 s[40:41], 1, v0
	s_cbranch_vccz .LBB0_131
	s_and_b64 vcc, exec, s[40:41]
	v_readlane_b32 s12, v247, 37
	s_cbranch_vccnz .LBB0_130
	s_lshl_b32 s3, s20, 2
	v_lshlrev_b32_e32 v178, 7, v177
	s_and_b32 s3, s3, 0xffffe000
	s_bfe_u32 s6, s20, 0x70004
	v_or_b32_e32 v194, 0x1e00, v178
	s_or_b32 s3, s3, s6
	v_or_b32_e32 v2, s3, v194
	v_mov_b64_e32 v[0:1], s[92:93]
	v_mad_i64_i32 v[2:3], s[6:7], v2, s33, v[0:1]
	s_lshl_b32 s6, s20, 7
	v_or_b32_e32 v193, 0x1c00, v178
	s_and_b32 s6, s6, 0x780
	s_mov_b32 s7, s96
	v_lshlrev_b32_e32 v154, 3, v176
	v_lshl_add_u64 v[2:3], v[2:3], 0, s[6:7]
	v_or_b32_e32 v4, s3, v193
	v_or_b32_e32 v192, 0x1a00, v178
	v_lshl_add_u64 v[2:3], v[2:3], 0, v[154:155]
	v_mad_i64_i32 v[4:5], s[8:9], v4, s33, v[0:1]
	v_add_co_u32_e32 v2, vcc, s46, v2
	v_lshl_add_u64 v[4:5], v[4:5], 0, s[6:7]
	v_or_b32_e32 v6, s3, v192
	v_or_b32_e32 v191, 0x1800, v178
	v_addc_co_u32_e32 v3, vcc, 0, v3, vcc
	v_lshl_add_u64 v[4:5], v[4:5], 0, v[154:155]
	v_mad_i64_i32 v[6:7], s[8:9], v6, s33, v[0:1]
	v_add_co_u32_e32 v4, vcc, s46, v4
	v_lshl_add_u64 v[6:7], v[6:7], 0, s[6:7]
	v_or_b32_e32 v8, s3, v191
	v_or_b32_e32 v190, 0x1600, v178
	v_addc_co_u32_e32 v5, vcc, 0, v5, vcc
	v_lshl_add_u64 v[6:7], v[6:7], 0, v[154:155]
	v_mad_i64_i32 v[8:9], s[8:9], v8, s33, v[0:1]
	v_add_co_u32_e32 v6, vcc, s46, v6
	v_lshl_add_u64 v[8:9], v[8:9], 0, s[6:7]
	v_or_b32_e32 v10, s3, v190
	v_or_b32_e32 v189, 0x1400, v178
	v_addc_co_u32_e32 v7, vcc, 0, v7, vcc
	v_lshl_add_u64 v[8:9], v[8:9], 0, v[154:155]
	v_mad_i64_i32 v[10:11], s[8:9], v10, s33, v[0:1]
	v_add_co_u32_e32 v8, vcc, s46, v8
	v_lshl_add_u64 v[10:11], v[10:11], 0, s[6:7]
	v_or_b32_e32 v12, s3, v189
	v_or_b32_e32 v188, 0x1200, v178
	v_addc_co_u32_e32 v9, vcc, 0, v9, vcc
	v_lshl_add_u64 v[10:11], v[10:11], 0, v[154:155]
	v_mad_i64_i32 v[12:13], s[8:9], v12, s33, v[0:1]
	v_add_co_u32_e32 v10, vcc, s46, v10
	v_lshl_add_u64 v[12:13], v[12:13], 0, s[6:7]
	v_or_b32_e32 v14, s3, v188
	v_or_b32_e32 v186, 0x1000, v178
	v_addc_co_u32_e32 v11, vcc, 0, v11, vcc
	v_lshl_add_u64 v[12:13], v[12:13], 0, v[154:155]
	v_mad_i64_i32 v[14:15], s[8:9], v14, s33, v[0:1]
	v_add_co_u32_e32 v12, vcc, s46, v12
	v_lshl_add_u64 v[14:15], v[14:15], 0, s[6:7]
	v_or_b32_e32 v16, s3, v186
	v_or_b32_e32 v185, 0xe00, v178
	v_addc_co_u32_e32 v13, vcc, 0, v13, vcc
	v_lshl_add_u64 v[14:15], v[14:15], 0, v[154:155]
	v_mad_i64_i32 v[16:17], s[8:9], v16, s33, v[0:1]
	v_add_co_u32_e32 v14, vcc, s46, v14
	v_lshl_add_u64 v[16:17], v[16:17], 0, s[6:7]
	v_or_b32_e32 v18, s3, v185
	v_or_b32_e32 v184, 0xc00, v178
	v_addc_co_u32_e32 v15, vcc, 0, v15, vcc
	v_lshl_add_u64 v[16:17], v[16:17], 0, v[154:155]
	v_mad_i64_i32 v[18:19], s[8:9], v18, s33, v[0:1]
	v_add_co_u32_e32 v16, vcc, s46, v16
	v_lshl_add_u64 v[18:19], v[18:19], 0, s[6:7]
	v_or_b32_e32 v20, s3, v184
	v_or_b32_e32 v183, 0xa00, v178
	v_addc_co_u32_e32 v17, vcc, 0, v17, vcc
	v_lshl_add_u64 v[18:19], v[18:19], 0, v[154:155]
	v_mad_i64_i32 v[20:21], s[8:9], v20, s33, v[0:1]
	v_add_co_u32_e32 v18, vcc, s46, v18
	v_lshl_add_u64 v[20:21], v[20:21], 0, s[6:7]
	v_or_b32_e32 v22, s3, v183
	v_or_b32_e32 v182, 0x800, v178
	v_addc_co_u32_e32 v19, vcc, 0, v19, vcc
	v_lshl_add_u64 v[20:21], v[20:21], 0, v[154:155]
	v_mad_i64_i32 v[22:23], s[8:9], v22, s33, v[0:1]
	v_add_co_u32_e32 v20, vcc, s46, v20
	v_lshl_add_u64 v[22:23], v[22:23], 0, s[6:7]
	v_or_b32_e32 v24, s3, v182
	v_or_b32_e32 v181, 0x600, v178
	v_addc_co_u32_e32 v21, vcc, 0, v21, vcc
	v_lshl_add_u64 v[22:23], v[22:23], 0, v[154:155]
	v_mad_i64_i32 v[24:25], s[8:9], v24, s33, v[0:1]
	v_add_co_u32_e32 v22, vcc, s46, v22
	v_lshl_add_u64 v[24:25], v[24:25], 0, s[6:7]
	v_or_b32_e32 v26, s3, v181
	v_or_b32_e32 v180, 0x400, v178
	v_addc_co_u32_e32 v23, vcc, 0, v23, vcc
	v_lshl_add_u64 v[24:25], v[24:25], 0, v[154:155]
	v_mad_i64_i32 v[26:27], s[8:9], v26, s33, v[0:1]
	v_add_co_u32_e32 v24, vcc, s46, v24
	v_lshl_add_u64 v[26:27], v[26:27], 0, s[6:7]
	v_or_b32_e32 v28, s3, v180
	v_or_b32_e32 v179, 0x200, v178
	v_addc_co_u32_e32 v25, vcc, 0, v25, vcc
	v_lshl_add_u64 v[26:27], v[26:27], 0, v[154:155]
	v_mad_i64_i32 v[28:29], s[8:9], v28, s33, v[0:1]
	v_add_co_u32_e32 v26, vcc, s46, v26
	v_lshl_add_u64 v[28:29], v[28:29], 0, s[6:7]
	v_or_b32_e32 v30, s3, v179
	v_addc_co_u32_e32 v27, vcc, 0, v27, vcc
	v_lshl_add_u64 v[28:29], v[28:29], 0, v[154:155]
	v_mad_i64_i32 v[30:31], s[8:9], v30, s33, v[0:1]
	v_add_co_u32_e32 v28, vcc, s46, v28
	v_lshl_add_u64 v[30:31], v[30:31], 0, s[6:7]
	v_or_b32_e32 v32, s3, v178
	v_addc_co_u32_e32 v29, vcc, 0, v29, vcc
	v_lshl_add_u64 v[30:31], v[30:31], 0, v[154:155]
	v_mad_i64_i32 v[0:1], s[8:9], v32, s33, v[0:1]
	v_add_co_u32_e32 v30, vcc, s46, v30
	v_lshl_add_u64 v[0:1], v[0:1], 0, s[6:7]
	s_nop 0
	v_addc_co_u32_e32 v31, vcc, 0, v31, vcc
	v_lshl_add_u64 v[0:1], v[0:1], 0, v[154:155]
	v_add_co_u32_e32 v0, vcc, s46, v0
	v_readlane_b32 s6, v245, 20
	s_nop 0
	v_addc_co_u32_e32 v1, vcc, 0, v1, vcc
	global_load_dwordx2 v[104:105], v[2:3], off offset:2048
	global_load_dwordx2 v[102:103], v[4:5], off offset:2048
	global_load_dwordx2 v[136:137], v[4:5], off
	global_load_dwordx2 v[146:147], v[2:3], off
	global_load_dwordx2 v[112:113], v[6:7], off offset:2048
	global_load_dwordx2 v[110:111], v[8:9], off offset:2048
	global_load_dwordx2 v[130:131], v[8:9], off
	global_load_dwordx2 v[144:145], v[6:7], off
	global_load_dwordx2 v[122:123], v[10:11], off offset:2048
	global_load_dwordx2 v[120:121], v[12:13], off offset:2048
	global_load_dwordx2 v[128:129], v[12:13], off
	global_load_dwordx2 v[142:143], v[10:11], off
	global_load_dwordx2 v[140:141], v[14:15], off offset:2048
	global_load_dwordx2 v[138:139], v[16:17], off offset:2048
	global_load_dwordx2 v[118:119], v[16:17], off
	global_load_dwordx2 v[132:133], v[14:15], off
	global_load_dwordx2 v[150:151], v[18:19], off offset:2048
	global_load_dwordx2 v[148:149], v[20:21], off offset:2048
	global_load_dwordx2 v[126:127], v[20:21], off
	global_load_dwordx2 v[134:135], v[18:19], off
	global_load_dwordx2 v[158:159], v[22:23], off offset:2048
	global_load_dwordx2 v[156:157], v[24:25], off offset:2048
	global_load_dwordx2 v[114:115], v[24:25], off
	global_load_dwordx2 v[124:125], v[22:23], off
	global_load_dwordx2 v[162:163], v[26:27], off offset:2048
	global_load_dwordx2 v[160:161], v[28:29], off offset:2048
	global_load_dwordx2 v[108:109], v[28:29], off
	global_load_dwordx2 v[116:117], v[26:27], off
	global_load_dwordx2 v[166:167], v[30:31], off offset:2048
	global_load_dwordx2 v[164:165], v[0:1], off offset:2048
	global_load_dwordx2 v[100:101], v[0:1], off
	global_load_dwordx2 v[106:107], v[30:31], off
	v_add_u32_e32 v1, s2, v154
	v_lshlrev_b32_e32 v154, 8, v176
	v_readlane_b32 s7, v245, 21
	v_lshlrev_b32_e32 v0, 2, v176
	s_lshl_b32 s3, s23, 6
	v_lshl_add_u64 v[2:3], s[6:7], 0, v[154:155]
	v_lshlrev_b32_e32 v154, 3, v177
	v_lshl_add_u64 v[2:3], v[2:3], 0, v[154:155]
	s_mov_b64 s[6:7], 0x2660000
	v_lshl_add_u64 v[96:97], v[2:3], 0, s[6:7]
	v_lshrrev_b32_e32 v2, 2, v201
	v_lshlrev_b32_e32 v3, 3, v201
	v_mul_u32_u24_e32 v2, 0x90, v2
	v_and_b32_e32 v3, 24, v3
	v_add3_u32 v195, s2, v2, v3
	v_mul_u32_u24_e32 v2, 0x90, v177
	v_readlane_b32 s6, v245, 0
	v_and_b32_e32 v196, 1, v200
	v_lshl_add_u64 v[98:99], s[4:5], 0, v[154:155]
	v_lshrrev_b32_e32 v197, 1, v176
	s_add_i32 s3, s6, s3
	v_add_u32_e32 v202, v1, v2
	v_lshlrev_b32_e32 v154, 1, v0
	s_mov_b32 s6, s20
	v_and_b32_e32 v220, 15, v199
	v_lshrrev_b32_e32 v221, 4, v199
	v_mul_u32_u24_e32 v216, 0x90, v220
	v_lshl_add_u32 v216, v221, 3, v216
	v_add_u32_e32 v216, s2, v216
	v_mul_u32_u24_e32 v217, 0x90, v221
	v_lshl_add_u32 v217, v220, 3, v217
	v_add_u32_e32 v217, s2, v217
	v_lshrrev_b32_e32 v222, 1, v221
	v_and_b32_e32 v223, 1, v221
	s_mov_b32 s98, 0x80800
	v_mul_lo_u32 v218, v222, s98
	v_lshl_add_u32 v218, v223, 11, v218
	v_lshl_add_u32 v218, v220, 3, v218
	v_add_u32_e32 v219, 0x101000, v218
	v_add_u32_e32 v228, 0x202000, v218
	v_add_u32_e32 v229, 0x303000, v218
.LBB0_129:
	v_add_u32_e32 v0, 0x800, v202
	s_waitcnt vmcnt(0)
	ds_write2_b64 v202, v[100:101], v[106:107] offset1:72
	ds_write2_b64 v202, v[108:109], v[116:117] offset0:144 offset1:216
	ds_write2_b64 v0, v[114:115], v[124:125] offset0:32 offset1:104
	ds_write2_b64 v0, v[126:127], v[134:135] offset0:176 offset1:248
	v_add_u32_e32 v0, 0x1000, v202
	ds_write2_b64 v0, v[118:119], v[132:133] offset0:64 offset1:136
	v_add_u32_e32 v0, 0x1400, v202
	ds_write2_b64 v0, v[128:129], v[142:143] offset0:80 offset1:152
	v_add_u32_e32 v0, 0x1800, v202
	ds_write2_b64 v0, v[130:131], v[144:145] offset0:96 offset1:168
	v_add_u32_e32 v0, 0x1c00, v202
	ds_write2_b64 v0, v[136:137], v[146:147] offset0:112 offset1:184
	v_add_u32_e32 v0, 0x2000, v202
	ds_write2_b64 v0, v[164:165], v[166:167] offset0:128 offset1:200
	v_add_u32_e32 v0, 0x2800, v202
	s_add_i32 s13, s6, s28
	ds_write2_b64 v0, v[160:161], v[162:163] offset0:16 offset1:88
	ds_write2_b64 v0, v[156:157], v[158:159] offset0:160 offset1:232
	v_add_u32_e32 v0, 0x3000, v202
	s_cmpk_lt_i32 s13, 0x1000
	ds_write2_b64 v0, v[148:149], v[150:151] offset0:48 offset1:120
	v_add_u32_e32 v0, 0x3400, v202
	s_cselect_b32 s7, s13, s6
	ds_write2_b64 v0, v[138:139], v[140:141] offset0:64 offset1:136
	v_add_u32_e32 v0, 0x3800, v202
	s_lshl_b32 s9, s7, 2
	ds_write2_b64 v0, v[120:121], v[122:123] offset0:80 offset1:152
	v_add_u32_e32 v0, 0x3c00, v202
	s_bfe_u32 s8, s7, 0x70004
	s_and_b32 s9, s9, 0xffffe000
	ds_write2_b64 v0, v[110:111], v[112:113] offset0:96 offset1:168
	v_add_u32_e32 v0, 0x4000, v202
	s_or_b32 s9, s9, s8
	ds_write2_b64 v0, v[102:103], v[104:105] offset0:112 offset1:184
	s_lshl_b32 s7, s7, 7
	v_or_b32_e32 v2, s9, v178
	v_mov_b64_e32 v[0:1], s[92:93]
	s_and_b32 s10, s7, 0x780
	v_mad_i64_i32 v[2:3], s[24:25], v2, s33, v[0:1]
	s_mov_b32 s11, s96
	v_lshl_add_u64 v[2:3], v[2:3], 0, s[10:11]
	v_or_b32_e32 v4, s9, v179
	v_lshl_add_u64 v[2:3], v[2:3], 0, v[154:155]
	v_mad_i64_i32 v[4:5], s[24:25], v4, s33, v[0:1]
	v_add_co_u32_e32 v2, vcc, s46, v2
	v_lshl_add_u64 v[4:5], v[4:5], 0, s[10:11]
	v_or_b32_e32 v6, s9, v180
	v_addc_co_u32_e32 v3, vcc, 0, v3, vcc
	v_lshl_add_u64 v[4:5], v[4:5], 0, v[154:155]
	v_mad_i64_i32 v[6:7], s[24:25], v6, s33, v[0:1]
	v_add_co_u32_e32 v4, vcc, s46, v4
	v_lshl_add_u64 v[6:7], v[6:7], 0, s[10:11]
	v_or_b32_e32 v8, s9, v181
	v_addc_co_u32_e32 v5, vcc, 0, v5, vcc
	v_lshl_add_u64 v[6:7], v[6:7], 0, v[154:155]
	v_mad_i64_i32 v[8:9], s[24:25], v8, s33, v[0:1]
	v_add_co_u32_e32 v6, vcc, s46, v6
	v_lshl_add_u64 v[8:9], v[8:9], 0, s[10:11]
	v_or_b32_e32 v10, s9, v182
	v_addc_co_u32_e32 v7, vcc, 0, v7, vcc
	v_lshl_add_u64 v[8:9], v[8:9], 0, v[154:155]
	v_mad_i64_i32 v[10:11], s[24:25], v10, s33, v[0:1]
	v_add_co_u32_e32 v8, vcc, s46, v8
	v_lshl_add_u64 v[10:11], v[10:11], 0, s[10:11]
	v_or_b32_e32 v12, s9, v183
	v_addc_co_u32_e32 v9, vcc, 0, v9, vcc
	v_lshl_add_u64 v[10:11], v[10:11], 0, v[154:155]
	v_mad_i64_i32 v[12:13], s[24:25], v12, s33, v[0:1]
	v_add_co_u32_e32 v10, vcc, s46, v10
	v_lshl_add_u64 v[12:13], v[12:13], 0, s[10:11]
	v_or_b32_e32 v14, s9, v184
	v_addc_co_u32_e32 v11, vcc, 0, v11, vcc
	v_lshl_add_u64 v[12:13], v[12:13], 0, v[154:155]
	v_mad_i64_i32 v[14:15], s[24:25], v14, s33, v[0:1]
	v_add_co_u32_e32 v12, vcc, s46, v12
	v_lshl_add_u64 v[14:15], v[14:15], 0, s[10:11]
	v_or_b32_e32 v16, s9, v185
	v_addc_co_u32_e32 v13, vcc, 0, v13, vcc
	v_lshl_add_u64 v[14:15], v[14:15], 0, v[154:155]
	v_mad_i64_i32 v[16:17], s[24:25], v16, s33, v[0:1]
	v_add_co_u32_e32 v14, vcc, s46, v14
	v_lshl_add_u64 v[16:17], v[16:17], 0, s[10:11]
	v_or_b32_e32 v18, s9, v186
	v_addc_co_u32_e32 v15, vcc, 0, v15, vcc
	v_lshl_add_u64 v[16:17], v[16:17], 0, v[154:155]
	v_mad_i64_i32 v[18:19], s[24:25], v18, s33, v[0:1]
	v_add_co_u32_e32 v16, vcc, s46, v16
	v_lshl_add_u64 v[18:19], v[18:19], 0, s[10:11]
	v_or_b32_e32 v20, s9, v188
	v_addc_co_u32_e32 v17, vcc, 0, v17, vcc
	v_lshl_add_u64 v[18:19], v[18:19], 0, v[154:155]
	v_mad_i64_i32 v[20:21], s[24:25], v20, s33, v[0:1]
	v_add_co_u32_e32 v18, vcc, s46, v18
	v_lshl_add_u64 v[20:21], v[20:21], 0, s[10:11]
	v_or_b32_e32 v22, s9, v189
	v_addc_co_u32_e32 v19, vcc, 0, v19, vcc
	v_lshl_add_u64 v[20:21], v[20:21], 0, v[154:155]
	v_mad_i64_i32 v[22:23], s[24:25], v22, s33, v[0:1]
	v_add_co_u32_e32 v20, vcc, s46, v20
	v_lshl_add_u64 v[22:23], v[22:23], 0, s[10:11]
	v_or_b32_e32 v24, s9, v190
	v_addc_co_u32_e32 v21, vcc, 0, v21, vcc
	v_lshl_add_u64 v[22:23], v[22:23], 0, v[154:155]
	v_mad_i64_i32 v[24:25], s[24:25], v24, s33, v[0:1]
	v_add_co_u32_e32 v22, vcc, s46, v22
	v_lshl_add_u64 v[24:25], v[24:25], 0, s[10:11]
	v_or_b32_e32 v26, s9, v191
	v_addc_co_u32_e32 v23, vcc, 0, v23, vcc
	v_lshl_add_u64 v[24:25], v[24:25], 0, v[154:155]
	v_mad_i64_i32 v[26:27], s[24:25], v26, s33, v[0:1]
	v_add_co_u32_e32 v24, vcc, s46, v24
	v_lshl_add_u64 v[26:27], v[26:27], 0, s[10:11]
	v_or_b32_e32 v28, s9, v192
	v_addc_co_u32_e32 v25, vcc, 0, v25, vcc
	v_lshl_add_u64 v[26:27], v[26:27], 0, v[154:155]
	v_mad_i64_i32 v[28:29], s[24:25], v28, s33, v[0:1]
	v_add_co_u32_e32 v26, vcc, s46, v26
	v_lshl_add_u64 v[28:29], v[28:29], 0, s[10:11]
	v_or_b32_e32 v30, s9, v193
	v_addc_co_u32_e32 v27, vcc, 0, v27, vcc
	v_lshl_add_u64 v[28:29], v[28:29], 0, v[154:155]
	v_mad_i64_i32 v[30:31], s[24:25], v30, s33, v[0:1]
	v_add_co_u32_e32 v28, vcc, s46, v28
	v_lshl_add_u64 v[30:31], v[30:31], 0, s[10:11]
	v_or_b32_e32 v32, s9, v194
	v_addc_co_u32_e32 v29, vcc, 0, v29, vcc
	v_lshl_add_u64 v[30:31], v[30:31], 0, v[154:155]
	v_mad_i64_i32 v[0:1], s[24:25], v32, s33, v[0:1]
	v_add_co_u32_e32 v30, vcc, s46, v30
	v_lshl_add_u64 v[0:1], v[0:1], 0, s[10:11]
	s_bfe_u32 s7, s6, 0x70004
	v_addc_co_u32_e32 v31, vcc, 0, v31, vcc
	v_lshl_add_u64 v[0:1], v[0:1], 0, v[154:155]
	s_lshl_b32 s8, s7, 15
	v_add_co_u32_e32 v0, vcc, s46, v0
	s_mov_b32 s9, s96
	s_nop 0
	v_addc_co_u32_e32 v1, vcc, 0, v1, vcc
	v_lshl_add_u64 v[170:171], v[96:97], 0, s[8:9]
	global_load_dwordx2 v[100:101], v[2:3], off
	global_load_dwordx2 v[106:107], v[4:5], off
	global_load_dwordx2 v[108:109], v[6:7], off
	global_load_dwordx2 v[116:117], v[8:9], off
	global_load_dwordx2 v[114:115], v[10:11], off
	global_load_dwordx2 v[124:125], v[12:13], off
	global_load_dwordx2 v[126:127], v[14:15], off
	global_load_dwordx2 v[134:135], v[16:17], off
	global_load_dwordx2 v[118:119], v[18:19], off
	global_load_dwordx2 v[132:133], v[20:21], off
	global_load_dwordx2 v[128:129], v[22:23], off
	global_load_dwordx2 v[142:143], v[24:25], off
	global_load_dwordx2 v[130:131], v[26:27], off
	global_load_dwordx2 v[144:145], v[28:29], off
	global_load_dwordx2 v[136:137], v[30:31], off
	global_load_dwordx2 v[146:147], v[0:1], off
	global_load_dwordx2 v[164:165], v[2:3], off offset:2048
	global_load_dwordx2 v[166:167], v[4:5], off offset:2048
	global_load_dwordx2 v[160:161], v[6:7], off offset:2048
	global_load_dwordx2 v[162:163], v[8:9], off offset:2048
	global_load_dwordx2 v[156:157], v[10:11], off offset:2048
	global_load_dwordx2 v[158:159], v[12:13], off offset:2048
	global_load_dwordx2 v[148:149], v[14:15], off offset:2048
	global_load_dwordx2 v[150:151], v[16:17], off offset:2048
	global_load_dwordx2 v[138:139], v[18:19], off offset:2048
	global_load_dwordx2 v[140:141], v[20:21], off offset:2048
	global_load_dwordx2 v[120:121], v[22:23], off offset:2048
	global_load_dwordx2 v[122:123], v[24:25], off offset:2048
	global_load_dwordx2 v[110:111], v[26:27], off offset:2048
	global_load_dwordx2 v[112:113], v[28:29], off offset:2048
	global_load_dwordx2 v[102:103], v[30:31], off offset:2048
	global_load_dwordx2 v[104:105], v[0:1], off offset:2048
	global_load_dwordx2 v[76:77], v[170:171], off
	global_load_dwordx2 v[78:79], v[170:171], off offset:32
	global_load_dwordx2 v[72:73], v[170:171], off offset:64
	global_load_dwordx2 v[74:75], v[170:171], off offset:96
	global_load_dwordx2 v[68:69], v[170:171], off offset:128
	global_load_dwordx2 v[70:71], v[170:171], off offset:160
	global_load_dwordx2 v[64:65], v[170:171], off offset:192
	global_load_dwordx2 v[66:67], v[170:171], off offset:224
	v_add_co_u32_e32 v82, vcc, s46, v170
	ds_read_b64_tr_b16 v[50:51], v195 offset:2304
	ds_read_b64_tr_b16 v[48:49], v195
	ds_read_b64_tr_b16 v[52:53], v195 offset:32
	ds_read_b64_tr_b16 v[54:55], v195 offset:2336
	ds_read_b64_tr_b16 v[56:57], v195 offset:64
	ds_read_b64_tr_b16 v[58:59], v195 offset:2368
	ds_read_b64_tr_b16 v[60:61], v195 offset:96
	ds_read_b64_tr_b16 v[62:63], v195 offset:2400
	ds_read_b64_tr_b16 v[32:33], v195 offset:4608
	ds_read_b64_tr_b16 v[34:35], v195 offset:6912
	ds_read_b64_tr_b16 v[36:37], v195 offset:4640
	ds_read_b64_tr_b16 v[38:39], v195 offset:6944
	ds_read_b64_tr_b16 v[40:41], v195 offset:4672
	ds_read_b64_tr_b16 v[42:43], v195 offset:6976
	ds_read_b64_tr_b16 v[44:45], v195 offset:4704
	ds_read_b64_tr_b16 v[46:47], v195 offset:7008
	ds_read_b64_tr_b16 v[16:17], v195 offset:9216
	ds_read_b64_tr_b16 v[18:19], v195 offset:11520
	ds_read_b64_tr_b16 v[20:21], v195 offset:9248
	ds_read_b64_tr_b16 v[22:23], v195 offset:11552
	ds_read_b64_tr_b16 v[24:25], v195 offset:9280
	ds_read_b64_tr_b16 v[26:27], v195 offset:11584
	ds_read_b64_tr_b16 v[28:29], v195 offset:9312
	ds_read_b64_tr_b16 v[30:31], v195 offset:11616
	ds_read_b64_tr_b16 v[0:1], v195 offset:13824
	ds_read_b64_tr_b16 v[2:3], v195 offset:16128
	ds_read_b64_tr_b16 v[4:5], v195 offset:13856
	ds_read_b64_tr_b16 v[6:7], v195 offset:16160
	ds_read_b64_tr_b16 v[8:9], v195 offset:13888
	ds_read_b64_tr_b16 v[10:11], v195 offset:16192
	ds_read_b64_tr_b16 v[12:13], v195 offset:13920
	ds_read_b64_tr_b16 v[14:15], v195 offset:16224
	v_addc_co_u32_e32 v83, vcc, 0, v171, vcc
	v_add_co_u32_e32 v174, vcc, s69, v170
	s_waitcnt vmcnt(6) lgkmcnt(14)
	v_mfma_f32_16x16x32_bf16 v[204:207], v[48:51], v[76:79], 0
	v_addc_co_u32_e32 v175, vcc, 0, v171, vcc
	global_load_dwordx2 v[92:93], v[174:175], off offset:-4096
	global_load_dwordx2 v[94:95], v[82:83], off offset:32
	global_load_dwordx2 v[88:89], v[82:83], off offset:64
	global_load_dwordx2 v[90:91], v[82:83], off offset:96
	global_load_dwordx2 v[84:85], v[82:83], off offset:128
	global_load_dwordx2 v[86:87], v[82:83], off offset:160
	global_load_dwordx2 v[80:81], v[82:83], off offset:192
	s_nop 0
	global_load_dwordx2 v[82:83], v[82:83], off offset:224
	v_mfma_f32_16x16x32_bf16 v[208:211], v[52:55], v[76:79], 0
	s_ashr_i32 s18, s6, 5
	s_and_b32 s6, s3, 0x3c0
	s_andn2_b32 s18, s18, 63
	v_mfma_f32_16x16x32_bf16 v[212:215], v[56:59], v[76:79], 0
	s_lshl_b32 s6, s6, 1
	v_lshl_or_b32 v172, s7, 1, v196
	s_mov_b32 s7, s96
	v_mfma_f32_16x16x32_bf16 v[76:79], v[60:63], v[76:79], 0
	v_lshl_add_u64 v[168:169], v[98:99], 0, s[6:7]
	v_or_b32_e32 v173, s18, v197
	s_movk_i32 s6, 0x101
	s_waitcnt vmcnt(12)
	v_mfma_f32_16x16x32_bf16 v[204:207], v[32:35], v[72:75], v[204:207]
	v_mad_u64_u32 v[172:173], s[6:7], v173, s6, v[172:173]
	v_ashrrev_i32_e32 v173, 31, v172
	v_mfma_f32_16x16x32_bf16 v[208:211], v[36:39], v[72:75], v[208:211]
	s_movk_i32 s6, 0x4000
	s_add_i32 s3, s3, s12
	s_cmpk_gt_i32 s13, 0xfff
	v_mfma_f32_16x16x32_bf16 v[212:215], v[40:43], v[72:75], v[212:215]
	v_mfma_f32_16x16x32_bf16 v[72:75], v[44:47], v[72:75], v[76:79]
	s_waitcnt vmcnt(10)
	v_mfma_f32_16x16x32_bf16 v[76:79], v[16:19], v[68:71], v[204:207]
	s_waitcnt lgkmcnt(12)
	v_mfma_f32_16x16x32_bf16 v[204:207], v[20:23], v[68:71], v[208:211]
	s_waitcnt lgkmcnt(10)
	v_mfma_f32_16x16x32_bf16 v[208:211], v[24:27], v[68:71], v[212:215]
	s_waitcnt lgkmcnt(8)
	v_mfma_f32_16x16x32_bf16 v[212:215], v[28:31], v[68:71], v[72:75]
	s_waitcnt vmcnt(8) lgkmcnt(6)
	v_mfma_f32_16x16x32_bf16 v[76:79], v[0:3], v[64:67], v[76:79]
	s_waitcnt lgkmcnt(4)
	v_mfma_f32_16x16x32_bf16 v[72:75], v[4:7], v[64:67], v[204:207]
	s_waitcnt lgkmcnt(2)
	v_mfma_f32_16x16x32_bf16 v[68:71], v[8:11], v[64:67], v[208:211]
	s_nop 0
	v_lshlrev_b64 v[204:205], 11, v[172:173]
	v_lshl_add_u64 v[204:205], v[168:169], 0, v[204:205]
	s_nop 0
	v_cvt_pk_bf16_f32 v76, v76, v77
	s_waitcnt lgkmcnt(0)
	v_mfma_f32_16x16x32_bf16 v[64:67], v[12:15], v[64:67], v[212:215]
	v_cvt_pk_bf16_f32 v77, v78, v79
	v_cvt_pk_bf16_f32 v72, v72, v73
	v_cvt_pk_bf16_f32 v73, v74, v75
	v_cvt_pk_bf16_f32 v68, v68, v69
	v_cvt_pk_bf16_f32 v69, v70, v71
	s_nop 2
	v_cvt_pk_bf16_f32 v64, v64, v65
	v_cvt_pk_bf16_f32 v65, v66, v67
	ds_write_b64 v216, v[76:77]
	ds_write_b64 v216, v[72:73] offset:32
	ds_write_b64 v216, v[68:69] offset:64
	ds_write_b64 v216, v[64:65] offset:96
	v_readfirstlane_b32 s98, v204
	v_readfirstlane_b32 s99, v205
	s_waitcnt lgkmcnt(0)
	ds_read_b64 v[220:221], v217
	ds_read_b64 v[222:223], v217 offset:576
	ds_read_b64 v[224:225], v217 offset:1152
	ds_read_b64 v[226:227], v217 offset:1728
	s_waitcnt lgkmcnt(3)
	global_store_dwordx2 v218, v[220:221], s[98:99]
	s_waitcnt lgkmcnt(2)
	global_store_dwordx2 v219, v[222:223], s[98:99]
	s_waitcnt lgkmcnt(1)
	global_store_dwordx2 v228, v[224:225], s[98:99]
	s_waitcnt lgkmcnt(0)
	global_store_dwordx2 v229, v[226:227], s[98:99]
	s_waitcnt vmcnt(10)
	v_mfma_f32_16x16x32_bf16 v[204:207], v[48:51], v[92:95], 0
	global_load_dwordx2 v[76:77], v[174:175], off
	global_load_dwordx2 v[78:79], v[174:175], off offset:32
	global_load_dwordx2 v[72:73], v[174:175], off offset:64
	global_load_dwordx2 v[74:75], v[174:175], off offset:96
	global_load_dwordx2 v[68:69], v[174:175], off offset:128
	global_load_dwordx2 v[70:71], v[174:175], off offset:160
	global_load_dwordx2 v[64:65], v[174:175], off offset:192
	global_load_dwordx2 v[66:67], v[174:175], off offset:224
	v_mfma_f32_16x16x32_bf16 v[208:211], v[52:55], v[92:95], 0
	v_mfma_f32_16x16x32_bf16 v[212:215], v[56:59], v[92:95], 0
	v_mfma_f32_16x16x32_bf16 v[92:95], v[60:63], v[92:95], 0
	s_waitcnt vmcnt(16)
	v_mfma_f32_16x16x32_bf16 v[204:207], v[32:35], v[88:91], v[204:207]
	v_mfma_f32_16x16x32_bf16 v[208:211], v[36:39], v[88:91], v[208:211]
	v_mfma_f32_16x16x32_bf16 v[212:215], v[40:43], v[88:91], v[212:215]
	v_mfma_f32_16x16x32_bf16 v[88:91], v[44:47], v[88:91], v[92:95]
	s_waitcnt vmcnt(14)
	v_mfma_f32_16x16x32_bf16 v[92:95], v[16:19], v[84:87], v[204:207]
	v_mfma_f32_16x16x32_bf16 v[204:207], v[20:23], v[84:87], v[208:211]
	v_mfma_f32_16x16x32_bf16 v[208:211], v[24:27], v[84:87], v[212:215]
	v_mfma_f32_16x16x32_bf16 v[84:87], v[28:31], v[84:87], v[88:91]
	s_waitcnt vmcnt(12)
	v_mfma_f32_16x16x32_bf16 v[88:91], v[0:3], v[80:83], v[92:95]
	v_mfma_f32_16x16x32_bf16 v[92:95], v[4:7], v[80:83], v[204:207]
	v_mfma_f32_16x16x32_bf16 v[204:207], v[8:11], v[80:83], v[208:211]
	v_mfma_f32_16x16x32_bf16 v[80:83], v[12:15], v[80:83], v[84:87]
	s_nop 2
	v_add_u32_e32 v84, 0x808, v172
	v_ashrrev_i32_e32 v85, 31, v84
	v_lshlrev_b64 v[84:85], 11, v[84:85]
	v_lshl_add_u64 v[84:85], v[168:169], 0, v[84:85]
	v_cvt_pk_bf16_f32 v86, v88, v89
	v_cvt_pk_bf16_f32 v87, v90, v91
	v_cvt_pk_bf16_f32 v80, v80, v81
	v_cvt_pk_bf16_f32 v81, v82, v83
	v_add_co_u32_e32 v82, vcc, s64, v170
	ds_write_b64 v216, v[86:87]
	v_cvt_pk_bf16_f32 v86, v92, v93
	v_cvt_pk_bf16_f32 v87, v94, v95
	v_addc_co_u32_e32 v83, vcc, 0, v171, vcc
	ds_write_b64 v216, v[86:87] offset:32
	v_cvt_pk_bf16_f32 v86, v204, v205
	v_cvt_pk_bf16_f32 v87, v206, v207
	v_add_co_u32_e32 v174, vcc, s6, v170
	ds_write_b64 v216, v[86:87] offset:64
	ds_write_b64 v216, v[80:81] offset:96
	v_readfirstlane_b32 s98, v84
	v_readfirstlane_b32 s99, v85
	s_waitcnt lgkmcnt(0)
	ds_read_b64 v[220:221], v217
	ds_read_b64 v[222:223], v217 offset:576
	ds_read_b64 v[224:225], v217 offset:1152
	ds_read_b64 v[226:227], v217 offset:1728
	s_waitcnt lgkmcnt(3)
	global_store_dwordx2 v218, v[220:221], s[98:99]
	s_waitcnt lgkmcnt(2)
	global_store_dwordx2 v219, v[222:223], s[98:99]
	s_waitcnt lgkmcnt(1)
	global_store_dwordx2 v228, v[224:225], s[98:99]
	s_waitcnt lgkmcnt(0)
	global_store_dwordx2 v229, v[226:227], s[98:99]
	v_addc_co_u32_e32 v175, vcc, 0, v171, vcc
	global_load_dwordx2 v[92:93], v[174:175], off offset:-4096
	global_load_dwordx2 v[94:95], v[82:83], off offset:32
	global_load_dwordx2 v[88:89], v[82:83], off offset:64
	global_load_dwordx2 v[90:91], v[82:83], off offset:96
	global_load_dwordx2 v[84:85], v[82:83], off offset:128
	global_load_dwordx2 v[86:87], v[82:83], off offset:160
	global_load_dwordx2 v[80:81], v[82:83], off offset:192
	s_nop 0
	global_load_dwordx2 v[82:83], v[82:83], off offset:224
	s_waitcnt vmcnt(18)
	v_mfma_f32_16x16x32_bf16 v[204:207], v[48:51], v[76:79], 0
	s_movk_i32 s6, 0x6000
	v_mfma_f32_16x16x32_bf16 v[208:211], v[52:55], v[76:79], 0
	v_mfma_f32_16x16x32_bf16 v[212:215], v[56:59], v[76:79], 0
	v_mfma_f32_16x16x32_bf16 v[76:79], v[60:63], v[76:79], 0
	s_waitcnt vmcnt(16)
	v_mfma_f32_16x16x32_bf16 v[204:207], v[32:35], v[72:75], v[204:207]
	v_mfma_f32_16x16x32_bf16 v[208:211], v[36:39], v[72:75], v[208:211]
	v_mfma_f32_16x16x32_bf16 v[212:215], v[40:43], v[72:75], v[212:215]
	v_mfma_f32_16x16x32_bf16 v[72:75], v[44:47], v[72:75], v[76:79]
	s_waitcnt vmcnt(14)
	v_mfma_f32_16x16x32_bf16 v[76:79], v[16:19], v[68:71], v[204:207]
	v_mfma_f32_16x16x32_bf16 v[204:207], v[20:23], v[68:71], v[208:211]
	v_mfma_f32_16x16x32_bf16 v[208:211], v[24:27], v[68:71], v[212:215]
	v_mfma_f32_16x16x32_bf16 v[68:71], v[28:31], v[68:71], v[72:75]
	s_waitcnt vmcnt(12)
	v_mfma_f32_16x16x32_bf16 v[72:75], v[0:3], v[64:67], v[76:79]
	v_mfma_f32_16x16x32_bf16 v[76:79], v[4:7], v[64:67], v[204:207]
	v_mfma_f32_16x16x32_bf16 v[204:207], v[8:11], v[64:67], v[208:211]
	v_mfma_f32_16x16x32_bf16 v[64:67], v[12:15], v[64:67], v[68:71]
	s_nop 2
	v_add_u32_e32 v68, 0x1010, v172
	v_ashrrev_i32_e32 v69, 31, v68
	v_lshlrev_b64 v[68:69], 11, v[68:69]
	v_lshl_add_u64 v[68:69], v[168:169], 0, v[68:69]
	v_cvt_pk_bf16_f32 v70, v72, v73
	v_cvt_pk_bf16_f32 v71, v74, v75
	ds_write_b64 v216, v[70:71]
	v_cvt_pk_bf16_f32 v70, v76, v77
	v_cvt_pk_bf16_f32 v71, v78, v79
	ds_write_b64 v216, v[70:71] offset:32
	v_cvt_pk_bf16_f32 v70, v204, v205
	v_cvt_pk_bf16_f32 v71, v206, v207
	v_cvt_pk_bf16_f32 v64, v64, v65
	v_cvt_pk_bf16_f32 v65, v66, v67
	s_waitcnt vmcnt(6)
	v_mfma_f32_16x16x32_bf16 v[204:207], v[48:51], v[92:95], 0
	ds_write_b64 v216, v[70:71] offset:64
	ds_write_b64 v216, v[64:65] offset:96
	v_readfirstlane_b32 s98, v68
	v_readfirstlane_b32 s99, v69
	s_waitcnt lgkmcnt(0)
	ds_read_b64 v[220:221], v217
	ds_read_b64 v[222:223], v217 offset:576
	ds_read_b64 v[224:225], v217 offset:1152
	ds_read_b64 v[226:227], v217 offset:1728
	s_waitcnt lgkmcnt(3)
	global_store_dwordx2 v218, v[220:221], s[98:99]
	s_waitcnt lgkmcnt(2)
	global_store_dwordx2 v219, v[222:223], s[98:99]
	s_waitcnt lgkmcnt(1)
	global_store_dwordx2 v228, v[224:225], s[98:99]
	s_waitcnt lgkmcnt(0)
	global_store_dwordx2 v229, v[226:227], s[98:99]
	global_load_dwordx2 v[76:77], v[174:175], off
	global_load_dwordx2 v[78:79], v[174:175], off offset:32
	global_load_dwordx2 v[72:73], v[174:175], off offset:64
	global_load_dwordx2 v[74:75], v[174:175], off offset:96
	s_nop 0
	global_load_dwordx2 v[68:69], v[174:175], off offset:128
	global_load_dwordx2 v[70:71], v[174:175], off offset:160
	global_load_dwordx2 v[64:65], v[174:175], off offset:192
	global_load_dwordx2 v[66:67], v[174:175], off offset:224
	v_mfma_f32_16x16x32_bf16 v[208:211], v[52:55], v[92:95], 0
	v_mfma_f32_16x16x32_bf16 v[212:215], v[56:59], v[92:95], 0
	v_mfma_f32_16x16x32_bf16 v[92:95], v[60:63], v[92:95], 0
	s_waitcnt vmcnt(16)
	v_mfma_f32_16x16x32_bf16 v[204:207], v[32:35], v[88:91], v[204:207]
	v_mfma_f32_16x16x32_bf16 v[208:211], v[36:39], v[88:91], v[208:211]
	v_mfma_f32_16x16x32_bf16 v[212:215], v[40:43], v[88:91], v[212:215]
	v_mfma_f32_16x16x32_bf16 v[88:91], v[44:47], v[88:91], v[92:95]
	s_waitcnt vmcnt(14)
	v_mfma_f32_16x16x32_bf16 v[92:95], v[16:19], v[84:87], v[204:207]
	v_mfma_f32_16x16x32_bf16 v[204:207], v[20:23], v[84:87], v[208:211]
	v_mfma_f32_16x16x32_bf16 v[208:211], v[24:27], v[84:87], v[212:215]
	v_mfma_f32_16x16x32_bf16 v[84:87], v[28:31], v[84:87], v[88:91]
	s_waitcnt vmcnt(12)
	v_mfma_f32_16x16x32_bf16 v[88:91], v[0:3], v[80:83], v[92:95]
	v_mfma_f32_16x16x32_bf16 v[92:95], v[4:7], v[80:83], v[204:207]
	v_mfma_f32_16x16x32_bf16 v[204:207], v[8:11], v[80:83], v[208:211]
	v_mfma_f32_16x16x32_bf16 v[80:83], v[12:15], v[80:83], v[84:87]
	s_nop 2
	v_add_u32_e32 v84, 0x1818, v172
	v_ashrrev_i32_e32 v85, 31, v84
	v_lshlrev_b64 v[84:85], 11, v[84:85]
	v_lshl_add_u64 v[84:85], v[168:169], 0, v[84:85]
	v_cvt_pk_bf16_f32 v86, v88, v89
	v_cvt_pk_bf16_f32 v87, v90, v91
	v_cvt_pk_bf16_f32 v80, v80, v81
	v_cvt_pk_bf16_f32 v81, v82, v83
	v_add_co_u32_e32 v82, vcc, s35, v170
	ds_write_b64 v216, v[86:87]
	v_cvt_pk_bf16_f32 v86, v92, v93
	v_cvt_pk_bf16_f32 v87, v94, v95
	v_addc_co_u32_e32 v83, vcc, 0, v171, vcc
	ds_write_b64 v216, v[86:87] offset:32
	v_cvt_pk_bf16_f32 v86, v204, v205
	v_cvt_pk_bf16_f32 v87, v206, v207
	v_add_co_u32_e32 v174, vcc, s6, v170
	ds_write_b64 v216, v[86:87] offset:64
	ds_write_b64 v216, v[80:81] offset:96
	v_readfirstlane_b32 s98, v84
	v_readfirstlane_b32 s99, v85
	s_waitcnt lgkmcnt(0)
	ds_read_b64 v[220:221], v217
	ds_read_b64 v[222:223], v217 offset:576
	ds_read_b64 v[224:225], v217 offset:1152
	ds_read_b64 v[226:227], v217 offset:1728
	s_waitcnt lgkmcnt(3)
	global_store_dwordx2 v218, v[220:221], s[98:99]
	s_waitcnt lgkmcnt(2)
	global_store_dwordx2 v219, v[222:223], s[98:99]
	s_waitcnt lgkmcnt(1)
	global_store_dwordx2 v228, v[224:225], s[98:99]
	s_waitcnt lgkmcnt(0)
	global_store_dwordx2 v229, v[226:227], s[98:99]
	v_addc_co_u32_e32 v175, vcc, 0, v171, vcc
	global_load_dwordx2 v[92:93], v[174:175], off offset:-4096
	global_load_dwordx2 v[94:95], v[82:83], off offset:32
	global_load_dwordx2 v[88:89], v[82:83], off offset:64
	global_load_dwordx2 v[90:91], v[82:83], off offset:96
	global_load_dwordx2 v[84:85], v[82:83], off offset:128
	global_load_dwordx2 v[86:87], v[82:83], off offset:160
	global_load_dwordx2 v[80:81], v[82:83], off offset:192
	s_nop 0
	global_load_dwordx2 v[82:83], v[82:83], off offset:224
	s_waitcnt vmcnt(18)
	v_mfma_f32_16x16x32_bf16 v[204:207], v[48:51], v[76:79], 0
	s_movk_i32 s6, 0x7000
	v_mfma_f32_16x16x32_bf16 v[208:211], v[52:55], v[76:79], 0
	v_mfma_f32_16x16x32_bf16 v[212:215], v[56:59], v[76:79], 0
	v_mfma_f32_16x16x32_bf16 v[76:79], v[60:63], v[76:79], 0
	s_waitcnt vmcnt(16)
	v_mfma_f32_16x16x32_bf16 v[204:207], v[32:35], v[72:75], v[204:207]
	v_mfma_f32_16x16x32_bf16 v[208:211], v[36:39], v[72:75], v[208:211]
	v_mfma_f32_16x16x32_bf16 v[212:215], v[40:43], v[72:75], v[212:215]
	v_mfma_f32_16x16x32_bf16 v[72:75], v[44:47], v[72:75], v[76:79]
	s_waitcnt vmcnt(14)
	v_mfma_f32_16x16x32_bf16 v[76:79], v[16:19], v[68:71], v[204:207]
	v_mfma_f32_16x16x32_bf16 v[204:207], v[20:23], v[68:71], v[208:211]
	v_mfma_f32_16x16x32_bf16 v[208:211], v[24:27], v[68:71], v[212:215]
	v_mfma_f32_16x16x32_bf16 v[68:71], v[28:31], v[68:71], v[72:75]
	s_waitcnt vmcnt(12)
	v_mfma_f32_16x16x32_bf16 v[72:75], v[0:3], v[64:67], v[76:79]
	v_mfma_f32_16x16x32_bf16 v[76:79], v[4:7], v[64:67], v[204:207]
	v_mfma_f32_16x16x32_bf16 v[204:207], v[8:11], v[64:67], v[208:211]
	v_mfma_f32_16x16x32_bf16 v[64:67], v[12:15], v[64:67], v[68:71]
	s_nop 2
	v_add_u32_e32 v68, 0x2020, v172
	v_ashrrev_i32_e32 v69, 31, v68
	v_lshlrev_b64 v[68:69], 11, v[68:69]
	v_lshl_add_u64 v[68:69], v[168:169], 0, v[68:69]
	v_cvt_pk_bf16_f32 v70, v72, v73
	v_cvt_pk_bf16_f32 v71, v74, v75
	ds_write_b64 v216, v[70:71]
	v_cvt_pk_bf16_f32 v70, v76, v77
	v_cvt_pk_bf16_f32 v71, v78, v79
	ds_write_b64 v216, v[70:71] offset:32
	v_cvt_pk_bf16_f32 v70, v204, v205
	v_cvt_pk_bf16_f32 v71, v206, v207
	s_waitcnt vmcnt(6)
	v_mfma_f32_16x16x32_bf16 v[204:207], v[48:51], v[92:95], 0
	v_cvt_pk_bf16_f32 v64, v64, v65
	v_cvt_pk_bf16_f32 v65, v66, v67
	ds_write_b64 v216, v[70:71] offset:64
	v_mfma_f32_16x16x32_bf16 v[208:211], v[52:55], v[92:95], 0
	ds_write_b64 v216, v[64:65] offset:96
	v_readfirstlane_b32 s98, v68
	v_readfirstlane_b32 s99, v69
	s_waitcnt lgkmcnt(0)
	ds_read_b64 v[220:221], v217
	ds_read_b64 v[222:223], v217 offset:576
	ds_read_b64 v[224:225], v217 offset:1152
	ds_read_b64 v[226:227], v217 offset:1728
	s_waitcnt lgkmcnt(3)
	global_store_dwordx2 v218, v[220:221], s[98:99]
	s_waitcnt lgkmcnt(2)
	global_store_dwordx2 v219, v[222:223], s[98:99]
	s_waitcnt lgkmcnt(1)
	global_store_dwordx2 v228, v[224:225], s[98:99]
	s_waitcnt lgkmcnt(0)
	global_store_dwordx2 v229, v[226:227], s[98:99]
	global_load_dwordx2 v[76:77], v[174:175], off
	global_load_dwordx2 v[78:79], v[174:175], off offset:32
	global_load_dwordx2 v[72:73], v[174:175], off offset:64
	global_load_dwordx2 v[74:75], v[174:175], off offset:96
	s_nop 0
	global_load_dwordx2 v[68:69], v[174:175], off offset:128
	global_load_dwordx2 v[70:71], v[174:175], off offset:160
	global_load_dwordx2 v[64:65], v[174:175], off offset:192
	global_load_dwordx2 v[66:67], v[174:175], off offset:224
	v_mfma_f32_16x16x32_bf16 v[212:215], v[56:59], v[92:95], 0
	v_mfma_f32_16x16x32_bf16 v[92:95], v[60:63], v[92:95], 0
	s_waitcnt vmcnt(16)
	v_mfma_f32_16x16x32_bf16 v[204:207], v[32:35], v[88:91], v[204:207]
	v_mfma_f32_16x16x32_bf16 v[208:211], v[36:39], v[88:91], v[208:211]
	v_mfma_f32_16x16x32_bf16 v[212:215], v[40:43], v[88:91], v[212:215]
	v_mfma_f32_16x16x32_bf16 v[88:91], v[44:47], v[88:91], v[92:95]
	s_waitcnt vmcnt(14)
	v_mfma_f32_16x16x32_bf16 v[92:95], v[16:19], v[84:87], v[204:207]
	v_mfma_f32_16x16x32_bf16 v[204:207], v[20:23], v[84:87], v[208:211]
	v_mfma_f32_16x16x32_bf16 v[208:211], v[24:27], v[84:87], v[212:215]
	v_mfma_f32_16x16x32_bf16 v[84:87], v[28:31], v[84:87], v[88:91]
	s_waitcnt vmcnt(12)
	v_mfma_f32_16x16x32_bf16 v[88:91], v[0:3], v[80:83], v[92:95]
	v_mfma_f32_16x16x32_bf16 v[92:95], v[4:7], v[80:83], v[204:207]
	v_mfma_f32_16x16x32_bf16 v[204:207], v[8:11], v[80:83], v[208:211]
	v_mfma_f32_16x16x32_bf16 v[80:83], v[12:15], v[80:83], v[84:87]
	s_nop 2
	v_add_u32_e32 v84, 0x2828, v172
	v_ashrrev_i32_e32 v85, 31, v84
	v_lshlrev_b64 v[84:85], 11, v[84:85]
	v_lshl_add_u64 v[84:85], v[168:169], 0, v[84:85]
	v_cvt_pk_bf16_f32 v86, v88, v89
	v_cvt_pk_bf16_f32 v87, v90, v91
	ds_write_b64 v216, v[86:87]
	v_cvt_pk_bf16_f32 v86, v92, v93
	v_cvt_pk_bf16_f32 v87, v94, v95
	ds_write_b64 v216, v[86:87] offset:32
	v_cvt_pk_bf16_f32 v86, v204, v205
	v_cvt_pk_bf16_f32 v87, v206, v207
	v_cvt_pk_bf16_f32 v80, v80, v81
	v_cvt_pk_bf16_f32 v81, v82, v83
	v_add_co_u32_e32 v82, vcc, s6, v170
	ds_write_b64 v216, v[86:87] offset:64
	ds_write_b64 v216, v[80:81] offset:96
	v_readfirstlane_b32 s98, v84
	v_readfirstlane_b32 s99, v85
	s_waitcnt lgkmcnt(0)
	ds_read_b64 v[220:221], v217
	ds_read_b64 v[222:223], v217 offset:576
	ds_read_b64 v[224:225], v217 offset:1152
	ds_read_b64 v[226:227], v217 offset:1728
	s_waitcnt lgkmcnt(3)
	global_store_dwordx2 v218, v[220:221], s[98:99]
	s_waitcnt lgkmcnt(2)
	global_store_dwordx2 v219, v[222:223], s[98:99]
	s_waitcnt lgkmcnt(1)
	global_store_dwordx2 v228, v[224:225], s[98:99]
	s_waitcnt lgkmcnt(0)
	global_store_dwordx2 v229, v[226:227], s[98:99]
	v_addc_co_u32_e32 v83, vcc, 0, v171, vcc
	global_load_dwordx2 v[92:93], v[82:83], off
	global_load_dwordx2 v[94:95], v[82:83], off offset:32
	global_load_dwordx2 v[88:89], v[82:83], off offset:64
	global_load_dwordx2 v[90:91], v[82:83], off offset:96
	global_load_dwordx2 v[84:85], v[82:83], off offset:128
	global_load_dwordx2 v[86:87], v[82:83], off offset:160
	global_load_dwordx2 v[80:81], v[82:83], off offset:192
	s_nop 0
	global_load_dwordx2 v[82:83], v[82:83], off offset:224
	s_waitcnt vmcnt(18)
	v_mfma_f32_16x16x32_bf16 v[204:207], v[48:51], v[76:79], 0
	s_mov_b32 s6, s13
	s_waitcnt vmcnt(6)
	v_mfma_f32_16x16x32_bf16 v[48:51], v[48:51], v[92:95], 0
	v_mfma_f32_16x16x32_bf16 v[208:211], v[52:55], v[76:79], 0
	v_mfma_f32_16x16x32_bf16 v[52:55], v[52:55], v[92:95], 0
	v_mfma_f32_16x16x32_bf16 v[212:215], v[56:59], v[76:79], 0
	v_mfma_f32_16x16x32_bf16 v[76:79], v[60:63], v[76:79], 0
	v_mfma_f32_16x16x32_bf16 v[56:59], v[56:59], v[92:95], 0
	v_mfma_f32_16x16x32_bf16 v[60:63], v[60:63], v[92:95], 0
	v_mfma_f32_16x16x32_bf16 v[204:207], v[32:35], v[72:75], v[204:207]
	s_waitcnt vmcnt(4)
	v_mfma_f32_16x16x32_bf16 v[32:35], v[32:35], v[88:91], v[48:51]
	v_mfma_f32_16x16x32_bf16 v[208:211], v[36:39], v[72:75], v[208:211]
	v_mfma_f32_16x16x32_bf16 v[36:39], v[36:39], v[88:91], v[52:55]
	v_mfma_f32_16x16x32_bf16 v[212:215], v[40:43], v[72:75], v[212:215]
	v_mfma_f32_16x16x32_bf16 v[72:75], v[44:47], v[72:75], v[76:79]
	v_mfma_f32_16x16x32_bf16 v[40:43], v[40:43], v[88:91], v[56:59]
	v_mfma_f32_16x16x32_bf16 v[44:47], v[44:47], v[88:91], v[60:63]
	v_mfma_f32_16x16x32_bf16 v[76:79], v[16:19], v[68:71], v[204:207]
	s_waitcnt vmcnt(2)
	v_mfma_f32_16x16x32_bf16 v[16:19], v[16:19], v[84:87], v[32:35]
	v_mfma_f32_16x16x32_bf16 v[204:207], v[20:23], v[68:71], v[208:211]
	v_mfma_f32_16x16x32_bf16 v[20:23], v[20:23], v[84:87], v[36:39]
	v_mfma_f32_16x16x32_bf16 v[208:211], v[24:27], v[68:71], v[212:215]
	v_mfma_f32_16x16x32_bf16 v[68:71], v[28:31], v[68:71], v[72:75]
	v_mfma_f32_16x16x32_bf16 v[24:27], v[24:27], v[84:87], v[40:43]
	v_mfma_f32_16x16x32_bf16 v[28:31], v[28:31], v[84:87], v[44:47]
	v_mfma_f32_16x16x32_bf16 v[72:75], v[0:3], v[64:67], v[76:79]
	s_waitcnt vmcnt(0)
	v_mfma_f32_16x16x32_bf16 v[0:3], v[0:3], v[80:83], v[16:19]
	v_mfma_f32_16x16x32_bf16 v[76:79], v[4:7], v[64:67], v[204:207]
	s_nop 1
	v_add_u32_e32 v16, 0x3838, v172
	v_ashrrev_i32_e32 v17, 31, v16
	v_lshlrev_b64 v[16:17], 11, v[16:17]
	v_mfma_f32_16x16x32_bf16 v[4:7], v[4:7], v[80:83], v[20:23]
	v_lshl_add_u64 v[16:17], v[168:169], 0, v[16:17]
	v_cvt_pk_bf16_f32 v0, v0, v1
	v_cvt_pk_bf16_f32 v1, v2, v3
	v_mfma_f32_16x16x32_bf16 v[204:207], v[8:11], v[64:67], v[208:211]
	ds_write_b64 v216, v[0:1]
	s_nop 2
	v_cvt_pk_bf16_f32 v0, v4, v5
	v_cvt_pk_bf16_f32 v1, v6, v7
	v_mfma_f32_16x16x32_bf16 v[64:67], v[12:15], v[64:67], v[68:71]
	ds_write_b64 v216, v[0:1] offset:32
	s_nop 1
	v_add_u32_e32 v68, 0x3030, v172
	v_mfma_f32_16x16x32_bf16 v[8:11], v[8:11], v[80:83], v[24:27]
	v_ashrrev_i32_e32 v69, 31, v68
	v_lshlrev_b64 v[68:69], 11, v[68:69]
	v_lshl_add_u64 v[68:69], v[168:169], 0, v[68:69]
	v_mfma_f32_16x16x32_bf16 v[12:15], v[12:15], v[80:83], v[28:31]
	v_cvt_pk_bf16_f32 v70, v72, v73
	v_cvt_pk_bf16_f32 v71, v74, v75
	ds_write_b64 v216, v[70:71] offset:2304
	v_cvt_pk_bf16_f32 v70, v76, v77
	v_cvt_pk_bf16_f32 v71, v78, v79
	v_cvt_pk_bf16_f32 v0, v8, v9
	v_cvt_pk_bf16_f32 v1, v10, v11
	ds_write_b64 v216, v[70:71] offset:2336
	v_cvt_pk_bf16_f32 v70, v204, v205
	v_cvt_pk_bf16_f32 v71, v206, v207
	v_cvt_pk_bf16_f32 v64, v64, v65
	v_cvt_pk_bf16_f32 v65, v66, v67
	ds_write_b64 v216, v[0:1] offset:64
	v_cvt_pk_bf16_f32 v0, v12, v13
	v_cvt_pk_bf16_f32 v1, v14, v15
	ds_write_b64 v216, v[70:71] offset:2368
	ds_write_b64 v216, v[64:65] offset:2400
	v_readfirstlane_b32 s100, v68
	v_readfirstlane_b32 s101, v69
	s_waitcnt lgkmcnt(0)
	ds_read_b64 v[230:231], v217 offset:2304
	ds_read_b64 v[232:233], v217 offset:2880
	ds_read_b64 v[234:235], v217 offset:3456
	ds_read_b64 v[236:237], v217 offset:4032
	s_waitcnt lgkmcnt(3)
	global_store_dwordx2 v218, v[230:231], s[100:101]
	s_waitcnt lgkmcnt(2)
	global_store_dwordx2 v219, v[232:233], s[100:101]
	s_waitcnt lgkmcnt(1)
	global_store_dwordx2 v228, v[234:235], s[100:101]
	s_waitcnt lgkmcnt(0)
	global_store_dwordx2 v229, v[236:237], s[100:101]
	ds_write_b64 v216, v[0:1] offset:96
	v_readfirstlane_b32 s98, v16
	v_readfirstlane_b32 s99, v17
	s_waitcnt lgkmcnt(0)
	ds_read_b64 v[220:221], v217
	ds_read_b64 v[222:223], v217 offset:576
	ds_read_b64 v[224:225], v217 offset:1152
	ds_read_b64 v[226:227], v217 offset:1728
	s_waitcnt lgkmcnt(3)
	global_store_dwordx2 v218, v[220:221], s[98:99]
	s_waitcnt lgkmcnt(2)
	global_store_dwordx2 v219, v[222:223], s[98:99]
	s_waitcnt lgkmcnt(1)
	global_store_dwordx2 v228, v[224:225], s[98:99]
	s_waitcnt lgkmcnt(0)
	global_store_dwordx2 v229, v[226:227], s[98:99]
	s_cbranch_scc0 .LBB0_129
